# gla_s3 q~S MFMA section: LDS fragment reads issued one MFMA pair ahead (two Q register sets), fills the MFMA shadow instead of wait-per-pair
# speedup vs baseline: 1.0022x; 1.0022x over previous
.LBB0_741:
	s_and_b32 s11, s24, 0x8000
	v_add_u32_e32 v160, s11, v187
	v_cvt_pk_bf16_f32 v220, v0, v1
	v_cvt_pk_bf16_f32 v221, v2, v3
	v_cvt_pk_bf16_f32 v222, v4, v5
	v_cvt_pk_bf16_f32 v223, v6, v7
	ds_read_b128 v[224:227], v160
	ds_read_b128 v[228:231], v160 offset:16384
	ds_read_b128 v[232:235], v160 offset:1024
	ds_read_b128 v[248:251], v160 offset:17408
	s_waitcnt lgkmcnt(2)
	v_mfma_f32_32x32x16_bf16 v[64:79], v[224:227], v[220:223], 0
	v_mfma_f32_32x32x16_bf16 v[80:95], v[228:231], v[220:223], 0
	v_cvt_pk_bf16_f32 v220, v8, v9
	v_cvt_pk_bf16_f32 v221, v10, v11
	v_cvt_pk_bf16_f32 v222, v12, v13
	v_cvt_pk_bf16_f32 v223, v14, v15
	ds_read_b128 v[224:227], v160 offset:2048
	ds_read_b128 v[228:231], v160 offset:18432
	s_waitcnt lgkmcnt(2)
	v_mfma_f32_32x32x16_bf16 v[64:79], v[232:235], v[220:223], v[64:79]
	v_mfma_f32_32x32x16_bf16 v[80:95], v[248:251], v[220:223], v[80:95]
	v_cvt_pk_bf16_f32 v220, v16, v17
	v_cvt_pk_bf16_f32 v221, v18, v19
	v_cvt_pk_bf16_f32 v222, v20, v21
	v_cvt_pk_bf16_f32 v223, v22, v23
	ds_read_b128 v[232:235], v160 offset:3072
	ds_read_b128 v[248:251], v160 offset:19456
	s_waitcnt lgkmcnt(2)
	v_mfma_f32_32x32x16_bf16 v[64:79], v[224:227], v[220:223], v[64:79]
	v_mfma_f32_32x32x16_bf16 v[80:95], v[228:231], v[220:223], v[80:95]
	v_cvt_pk_bf16_f32 v220, v24, v25
	v_cvt_pk_bf16_f32 v221, v26, v27
	v_cvt_pk_bf16_f32 v222, v28, v29
	v_cvt_pk_bf16_f32 v223, v30, v31
	ds_read_b128 v[224:227], v160 offset:4096
	ds_read_b128 v[228:231], v160 offset:20480
	s_waitcnt lgkmcnt(2)
	v_mfma_f32_32x32x16_bf16 v[64:79], v[232:235], v[220:223], v[64:79]
	v_mfma_f32_32x32x16_bf16 v[80:95], v[248:251], v[220:223], v[80:95]
	v_cvt_pk_bf16_f32 v220, v32, v33
	v_cvt_pk_bf16_f32 v221, v34, v35
	v_cvt_pk_bf16_f32 v222, v36, v37
	v_cvt_pk_bf16_f32 v223, v38, v39
	ds_read_b128 v[232:235], v160 offset:5120
	ds_read_b128 v[248:251], v160 offset:21504
	s_waitcnt lgkmcnt(2)
	v_mfma_f32_32x32x16_bf16 v[64:79], v[224:227], v[220:223], v[64:79]
	v_mfma_f32_32x32x16_bf16 v[80:95], v[228:231], v[220:223], v[80:95]
	v_cvt_pk_bf16_f32 v220, v40, v41
	v_cvt_pk_bf16_f32 v221, v42, v43
	v_cvt_pk_bf16_f32 v222, v44, v45
	v_cvt_pk_bf16_f32 v223, v46, v47
	ds_read_b128 v[224:227], v160 offset:6144
	ds_read_b128 v[228:231], v160 offset:22528
	s_waitcnt lgkmcnt(2)
	v_mfma_f32_32x32x16_bf16 v[64:79], v[232:235], v[220:223], v[64:79]
	v_mfma_f32_32x32x16_bf16 v[80:95], v[248:251], v[220:223], v[80:95]
	v_cvt_pk_bf16_f32 v220, v48, v49
	v_cvt_pk_bf16_f32 v221, v50, v51
	v_cvt_pk_bf16_f32 v222, v52, v53
	v_cvt_pk_bf16_f32 v223, v54, v55
	ds_read_b128 v[232:235], v160 offset:7168
	ds_read_b128 v[248:251], v160 offset:23552
	s_waitcnt lgkmcnt(2)
	v_mfma_f32_32x32x16_bf16 v[64:79], v[224:227], v[220:223], v[64:79]
	v_mfma_f32_32x32x16_bf16 v[80:95], v[228:231], v[220:223], v[80:95]
	v_cvt_pk_bf16_f32 v220, v56, v57
	v_cvt_pk_bf16_f32 v221, v58, v59
	v_cvt_pk_bf16_f32 v222, v60, v61
	v_cvt_pk_bf16_f32 v223, v62, v63
	s_nop 1
	s_waitcnt lgkmcnt(0)
	v_mfma_f32_32x32x16_bf16 v[64:79], v[232:235], v[220:223], v[64:79]
	v_mfma_f32_32x32x16_bf16 v[80:95], v[248:251], v[220:223], v[80:95]
	s_nop 11
	v_cndmask_b32_e64 v160, v64, v80, s[6:7]
	v_cndmask_b32_e64 v203, v65, v81, s[6:7]
	v_cndmask_b32_e64 v205, v66, v82, s[6:7]
	v_cndmask_b32_e64 v207, v67, v83, s[6:7]
	v_cndmask_b32_e64 v209, v68, v84, s[6:7]
	v_cndmask_b32_e64 v211, v69, v85, s[6:7]
	v_cndmask_b32_e64 v220, v70, v86, s[6:7]
	v_cndmask_b32_e64 v221, v71, v87, s[6:7]
	v_cndmask_b32_e64 v222, v72, v88, s[6:7]
	v_cndmask_b32_e64 v223, v73, v89, s[6:7]
	v_cndmask_b32_e64 v224, v74, v90, s[6:7]
	v_cndmask_b32_e64 v225, v75, v91, s[6:7]
	v_cndmask_b32_e64 v226, v76, v92, s[6:7]
	v_cndmask_b32_e64 v227, v77, v93, s[6:7]
	v_cndmask_b32_e64 v228, v78, v94, s[6:7]
	v_cndmask_b32_e64 v229, v79, v95, s[6:7]
	ds_write2st64_b32 v181, v160, v203 offset0:64 offset1:65
	ds_write2st64_b32 v181, v205, v207 offset0:66 offset1:67
	ds_write2st64_b32 v181, v209, v211 offset0:68 offset1:69
	ds_write2st64_b32 v181, v220, v221 offset0:70 offset1:71
	ds_write2st64_b32 v181, v222, v223 offset0:72 offset1:73
	ds_write2st64_b32 v181, v224, v225 offset0:74 offset1:75
	ds_write2st64_b32 v181, v226, v227 offset0:76 offset1:77
	ds_write2st64_b32 v181, v228, v229 offset0:78 offset1:79
	s_waitcnt vmcnt(10)
	ds_write_b128 v183, v[100:103]
	ds_write_b128 v183, v[108:111] offset:8192
	ds_write_b128 v183, v[116:119] offset:16384
	ds_write_b128 v183, v[124:127] offset:24576
	s_and_saveexec_b64 s[4:5], s[0:1]
	ds_write_b32 v185, v201
	s_or_b64 exec, exec, s[4:5]
	s_waitcnt lgkmcnt(0)
	s_barrier
	ds_read2st64_b32 v[234:235], v191 offset1:1
	ds_read2st64_b32 v[232:233], v191 offset0:2 offset1:3
	ds_read2st64_b32 v[230:231], v191 offset0:4 offset1:5
	ds_read2st64_b32 v[228:229], v191 offset0:6 offset1:7
	ds_read2st64_b32 v[226:227], v191 offset0:8 offset1:9
	ds_read2st64_b32 v[224:225], v191 offset0:10 offset1:11
	ds_read2st64_b32 v[222:223], v191 offset0:12 offset1:13
	ds_read2st64_b32 v[220:221], v191 offset0:14 offset1:15
	v_cndmask_b32_e64 v160, 0, 1, s[14:15]
	v_cmp_ne_u32_e64 s[4:5], 1, v160
	s_andn2_b64 vcc, exec, s[14:15]
	s_cbranch_vccnz .Lmy_s3_last
	s_add_i32 s14, s10, 4
	s_ashr_i32 s15, s14, 31
	s_lshl_b64 s[16:17], s[14:15], 15
	v_lshl_add_u64 v[116:117], v[172:173], 0, s[16:17]
	v_add_co_u32_e32 v108, vcc, 0x2000, v116
	s_nop 1
	v_addc_co_u32_e32 v109, vcc, 0, v117, vcc
	v_add_co_u32_e32 v118, vcc, 0x4000, v116
	global_load_dwordx4 v[100:103], v[116:117], off
	s_nop 0
	global_load_dwordx4 v[108:111], v[108:109], off
	v_addc_co_u32_e32 v119, vcc, 0, v117, vcc
	v_add_co_u32_e32 v124, vcc, 0x6000, v116
	s_nop 1
	v_addc_co_u32_e32 v125, vcc, 0, v117, vcc
	global_load_dwordx4 v[116:119], v[118:119], off
	s_nop 0
	global_load_dwordx4 v[124:127], v[124:125], off
	s_and_saveexec_b64 s[16:17], s[0:1]
	s_cbranch_execz .LBB0_746
	s_lshl_b64 s[14:15], s[14:15], 10
	v_lshl_add_u64 v[240:241], v[174:175], 0, s[14:15]
	global_load_dword v201, v[240:241], off
